# attention: transcendentals kept out of the post-barrier head of the second QK block (exp interleaved 1:1 with the dependent row-sum adds); PV gap fill budgeted at 24 issue cycles per MFMA
# baseline (speedup 1.0000x reference)
.LBB0_217:
	v_mfma_f32_32x32x16_bf16 v[32:47], v[100:103], v[112:115], v[32:47]
	v_max_f32_e32 v252, v85, v85
	v_max_f32_e32 v253, v84, v84
	v_max_f32_e32 v252, v253, v252
	v_max3_f32 v252, v252, v86, v87
	v_max3_f32 v252, v252, v88, v89
	v_max3_f32 v252, v252, v90, v91
	ds_read_b64_tr_b16 v[112:113], v211 offset:0x200
	ds_read_b64_tr_b16 v[114:115], v211 offset:0xa00
	v_mfma_f32_32x32x16_bf16 v[32:47], v[64:67], v[116:119], v[32:47]
	v_max3_f32 v252, v252, v92, v93
	v_max3_f32 v252, v252, v94, v95
	v_max3_f32 v252, v252, v96, v97
	v_max3_f32 v252, v252, v98, v99
	v_max3_f32 v252, v252, v68, v69
	v_max3_f32 v252, v252, v70, v71
	ds_read_b64_tr_b16 v[116:117], v211 offset:0x1200
	ds_read_b64_tr_b16 v[118:119], v211 offset:0x1a00
	v_mfma_f32_32x32x16_bf16 v[32:47], v[104:107], v[120:123], v[32:47]
	v_max3_f32 v252, v252, v72, v73
	v_max3_f32 v252, v252, v74, v75
	v_max3_f32 v252, v252, v76, v77
	v_max3_f32 v252, v252, v78, v79
	v_max3_f32 v252, v252, v80, v81
	v_max3_f32 v252, v252, v82, v83
	ds_read_b64_tr_b16 v[120:121], v211 offset:0x2200
	ds_read_b64_tr_b16 v[122:123], v211 offset:0x2a00
	ds_read_b64_tr_b16 v[178:179], v211 offset:0x3200
	ds_read_b64_tr_b16 v[180:181], v211 offset:0x3a00
	s_waitcnt lgkmcnt(0)
	v_mfma_f32_32x32x16_bf16 v[32:47], v[108:111], v[124:127], v[32:47]
	v_mov_b32_e32 v253, v252
	s_nop 1
	v_permlane32_swap_b32_e32 v252, v253
	v_max_f32_e32 v253, v253, v253
	v_max_f32_e32 v252, v252, v252
	v_max_f32_e32 v252, v252, v253
	v_mfma_f32_32x32x16_bf16 v[48:63], v[100:103], v[112:115], v[48:63]
	v_max_f32_e32 v255, v176, v176
	v_sub_f32_e32 v253, v252, v176
	v_max_f32_e32 v252, v255, v252
	v_sub_f32_e32 v255, v176, v252
	v_mul_f32_e32 v255, 0x3e0293ee, v255
	v_mul_f32_e32 v253, 0x3db504f3, v253
	ds_read_b64_tr_b16 v[112:113], v211 offset:0x400
	ds_read_b64_tr_b16 v[114:115], v211 offset:0xc00
	v_mfma_f32_32x32x16_bf16 v[48:63], v[64:67], v[116:119], v[48:63]
	v_exp_f32_e32 v255, v255
	v_cmp_ge_f32_e32 vcc, s82, v253
	s_cmp_eq_u64 vcc, exec
	s_cselect_b64 s[4:5], -1, 0
	v_cndmask_b32_e64 v227, v252, v176, s[4:5]
	ds_read_b64_tr_b16 v[116:117], v211 offset:0x1400
	ds_read_b64_tr_b16 v[118:119], v211 offset:0x1c00
	v_mfma_f32_32x32x16_bf16 v[48:63], v[104:107], v[120:123], v[48:63]
	v_mul_f32_e32 v176, 0xbe0293ee, v227
	v_fmamk_f32 v232, v84, 0x3e0293ee, v176
	v_fmamk_f32 v233, v85, 0x3e0293ee, v176
	v_fmamk_f32 v234, v86, 0x3e0293ee, v176
	v_fmamk_f32 v235, v87, 0x3e0293ee, v176
	v_fmamk_f32 v236, v88, 0x3e0293ee, v176
	ds_read_b64_tr_b16 v[120:121], v211 offset:0x2400
	ds_read_b64_tr_b16 v[122:123], v211 offset:0x2c00
	ds_read_b64_tr_b16 v[124:125], v211 offset:0x3400
	ds_read_b64_tr_b16 v[126:127], v211 offset:0x3c00
	s_waitcnt lgkmcnt(0)
	v_mfma_f32_32x32x16_bf16 v[48:63], v[108:111], v[178:181], v[48:63]
	v_fmamk_f32 v237, v89, 0x3e0293ee, v176
	v_fmamk_f32 v238, v90, 0x3e0293ee, v176
	v_fmamk_f32 v239, v91, 0x3e0293ee, v176
	v_fmamk_f32 v240, v92, 0x3e0293ee, v176
	v_fmamk_f32 v241, v93, 0x3e0293ee, v176
	v_fmamk_f32 v242, v94, 0x3e0293ee, v176
	v_mfma_f32_32x32x16_bf16 v[16:31], v[100:103], v[112:115], v[16:31]
	v_fmamk_f32 v243, v95, 0x3e0293ee, v176
	v_fmamk_f32 v96, v96, 0x3e0293ee, v176
	v_fmamk_f32 v97, v97, 0x3e0293ee, v176
	v_fmamk_f32 v98, v98, 0x3e0293ee, v176
	v_fmamk_f32 v99, v99, 0x3e0293ee, v176
	v_fmamk_f32 v84, v68, 0x3e0293ee, v176
	ds_read_b64_tr_b16 v[112:113], v211 offset:0x600
	ds_read_b64_tr_b16 v[114:115], v211 offset:0xe00
	v_mfma_f32_32x32x16_bf16 v[16:31], v[64:67], v[116:119], v[16:31]
	v_fmamk_f32 v93, v69, 0x3e0293ee, v176
	v_fmamk_f32 v94, v70, 0x3e0293ee, v176
	v_fmamk_f32 v95, v71, 0x3e0293ee, v176
	v_fmamk_f32 v177, v72, 0x3e0293ee, v176
	v_fmamk_f32 v85, v73, 0x3e0293ee, v176
	v_fmamk_f32 v86, v74, 0x3e0293ee, v176
	ds_read_b64_tr_b16 v[116:117], v211 offset:0x1600
	ds_read_b64_tr_b16 v[118:119], v211 offset:0x1e00
	v_mfma_f32_32x32x16_bf16 v[16:31], v[104:107], v[120:123], v[16:31]
	v_fmamk_f32 v87, v75, 0x3e0293ee, v176
	v_fmamk_f32 v88, v76, 0x3e0293ee, v176
	v_fmamk_f32 v89, v77, 0x3e0293ee, v176
	v_fmamk_f32 v90, v78, 0x3e0293ee, v176
	v_fmamk_f32 v91, v79, 0x3e0293ee, v176
	ds_read_b64_tr_b16 v[120:121], v211 offset:0x2600
	ds_read_b64_tr_b16 v[122:123], v211 offset:0x2e00
	ds_read_b64_tr_b16 v[178:179], v211 offset:0x3600
	ds_read_b64_tr_b16 v[180:181], v211 offset:0x3e00
	s_waitcnt lgkmcnt(0)
	v_mfma_f32_32x32x16_bf16 v[16:31], v[108:111], v[124:127], v[16:31]
	v_exp_f32_e32 v68, v236
	v_exp_f32_e32 v69, v237
	v_exp_f32_e32 v70, v238
	v_mfma_f32_32x32x16_bf16 v[0:15], v[100:103], v[112:115], v[0:15]
	v_exp_f32_e32 v71, v239
	v_exp_f32_e32 v72, v240
	v_exp_f32_e32 v73, v241
	v_mfma_f32_32x32x16_bf16 v[0:15], v[64:67], v[116:119], v[0:15]
	v_exp_f32_e32 v64, v232
	v_exp_f32_e32 v65, v233
	v_exp_f32_e32 v66, v234
	v_mfma_f32_32x32x16_bf16 v[0:15], v[104:107], v[120:123], v[0:15]
	v_exp_f32_e32 v67, v235
	v_exp_f32_e32 v74, v242
	v_exp_f32_e32 v75, v243
	v_mfma_f32_32x32x16_bf16 v[0:15], v[108:111], v[178:181], v[0:15]
	v_exp_f32_e32 v76, v96
	v_exp_f32_e32 v77, v97
	v_exp_f32_e32 v78, v98
	v_exp_f32_e32 v79, v99
	v_fmamk_f32 v92, v80, 0x3e0293ee, v176
	v_fmamk_f32 v178, v81, 0x3e0293ee, v176
	v_fmamk_f32 v179, v82, 0x3e0293ee, v176
	v_fmac_f32_e32 v176, 0x3e0293ee, v83
	s_waitcnt vmcnt(0)
	ds_write_b128 v213, v[168:171] offset:32768
	ds_write_b128 v213, v[172:175] offset:40960
	s_barrier
	s_waitcnt vmcnt(0)
	v_cndmask_b32_e64 v225, v255, 1.0, s[4:5]
	v_cmp_gt_f32_e32 vcc, 1.0, v225
	s_waitcnt vmcnt(3)
	ds_write_b128 v199, v[160:163]
	s_waitcnt vmcnt(2)
	ds_write_b128 v216, v[164:167]
	s_cbranch_vccz .LBB0_221
	s_and_saveexec_b64 s[72:73], s[0:1]
	ds_write_b32 v214, v225 offset:128
	s_or_b64 exec, exec, s[72:73]
	s_waitcnt lgkmcnt(0)
	ds_read_b128 v[100:103], v212 offset:224
	ds_read_b128 v[104:107], v212 offset:192
	ds_read_b128 v[108:111], v212 offset:160
	ds_read_b128 v[112:115], v212 offset:128
	s_waitcnt lgkmcnt(3)
	v_pk_mul_f32 v[46:47], v[46:47], v[102:103]
	s_waitcnt lgkmcnt(2)
	v_pk_mul_f32 v[42:43], v[42:43], v[106:107]
	s_waitcnt lgkmcnt(1)
	v_pk_mul_f32 v[38:39], v[38:39], v[110:111]
	s_waitcnt lgkmcnt(0)
	v_pk_mul_f32 v[34:35], v[34:35], v[114:115]
	v_pk_mul_f32 v[44:45], v[44:45], v[100:101]
	v_pk_mul_f32 v[40:41], v[40:41], v[104:105]
	v_pk_mul_f32 v[36:37], v[36:37], v[108:109]
	v_pk_mul_f32 v[32:33], v[32:33], v[112:113]
	v_pk_mul_f32 v[62:63], v[62:63], v[102:103]
	v_pk_mul_f32 v[58:59], v[58:59], v[106:107]
	v_pk_mul_f32 v[54:55], v[54:55], v[110:111]
	v_pk_mul_f32 v[50:51], v[50:51], v[114:115]
	v_pk_mul_f32 v[60:61], v[60:61], v[100:101]
	v_pk_mul_f32 v[56:57], v[56:57], v[104:105]
	v_pk_mul_f32 v[52:53], v[52:53], v[108:109]
	v_pk_mul_f32 v[48:49], v[48:49], v[112:113]
	v_pk_mul_f32 v[30:31], v[30:31], v[102:103]
	v_pk_mul_f32 v[26:27], v[26:27], v[106:107]
	v_pk_mul_f32 v[22:23], v[22:23], v[110:111]
	v_pk_mul_f32 v[18:19], v[18:19], v[114:115]
	v_pk_mul_f32 v[28:29], v[28:29], v[100:101]
	v_pk_mul_f32 v[24:25], v[24:25], v[104:105]
	v_pk_mul_f32 v[20:21], v[20:21], v[108:109]
	v_pk_mul_f32 v[16:17], v[16:17], v[112:113]
	v_pk_mul_f32 v[14:15], v[14:15], v[102:103]
	v_pk_mul_f32 v[10:11], v[10:11], v[106:107]
	v_pk_mul_f32 v[6:7], v[6:7], v[110:111]
	v_pk_mul_f32 v[2:3], v[2:3], v[114:115]
	v_pk_mul_f32 v[12:13], v[12:13], v[100:101]
	v_pk_mul_f32 v[8:9], v[8:9], v[104:105]
	v_pk_mul_f32 v[4:5], v[4:5], v[108:109]
	v_pk_mul_f32 v[0:1], v[0:1], v[112:113]
.LBB0_221:
	s_waitcnt lgkmcnt(0)
	s_barrier
	ds_read_b128 v[232:235], v197 offset:32768
	ds_read_b128 v[96:99], v197 offset:40960
	ds_read_b128 v[236:239], v217 offset:32768
	ds_read_b128 v[240:243], v217 offset:40960
	v_exp_f32_e32 v83, v95
	v_exp_f32_e32 v95, v176
	v_add_f32_e32 v176, 0, v64
	s_waitcnt lgkmcnt(3)
	v_mfma_f32_32x32x16_bf16 v[112:127], v[232:235], v[156:159], 0
	ds_read_b128 v[244:247], v218 offset:32768
	v_add_f32_e32 v176, v65, v176
	v_add_f32_e32 v176, v66, v176
	v_add_f32_e32 v176, v67, v176
	v_add_f32_e32 v176, v68, v176
	v_add_f32_e32 v176, v69, v176
	s_waitcnt lgkmcnt(3)
	v_mfma_f32_32x32x16_bf16 v[96:111], v[96:99], v[156:159], 0
	ds_read_b128 v[248:251], v218 offset:40960
	v_add_f32_e32 v176, v70, v176
	v_add_f32_e32 v176, v71, v176
	v_add_f32_e32 v176, v72, v176
	v_add_f32_e32 v176, v73, v176
	v_add_f32_e32 v176, v74, v176
	s_waitcnt lgkmcnt(3)
	v_mfma_f32_32x32x16_bf16 v[112:127], v[236:239], v[152:155], v[112:127]
	ds_read_b128 v[232:235], v219 offset:32768
	v_add_f32_e32 v176, v75, v176
	v_add_f32_e32 v176, v76, v176
	v_add_f32_e32 v176, v77, v176
	v_add_f32_e32 v176, v78, v176
	v_add_f32_e32 v176, v79, v176
	s_waitcnt lgkmcnt(3)
	v_mfma_f32_32x32x16_bf16 v[96:111], v[240:243], v[152:155], v[96:111]
	ds_read_b128 v[236:239], v219 offset:40960
	v_exp_f32_e32 v80, v84
	v_exp_f32_e32 v81, v93
	v_add_f32_e32 v176, v80, v176
	v_exp_f32_e32 v82, v94
	v_add_f32_e32 v176, v81, v176
	s_waitcnt lgkmcnt(3)
	v_mfma_f32_32x32x16_bf16 v[112:127], v[244:247], v[148:151], v[112:127]
	ds_read_b128 v[240:243], v197 offset:32896
	v_exp_f32_e32 v84, v177
	v_add_f32_e32 v176, v82, v176
	v_exp_f32_e32 v85, v85
	v_add_f32_e32 v176, v83, v176
	v_exp_f32_e32 v86, v86
	s_waitcnt lgkmcnt(3)
	v_mfma_f32_32x32x16_bf16 v[96:111], v[248:251], v[148:151], v[96:111]
	ds_read_b128 v[244:247], v197 offset:41088
	v_add_f32_e32 v176, v84, v176
	v_exp_f32_e32 v87, v87
	v_add_f32_e32 v176, v85, v176
	v_exp_f32_e32 v88, v88
	v_add_f32_e32 v176, v86, v176
	s_waitcnt lgkmcnt(3)
	v_mfma_f32_32x32x16_bf16 v[112:127], v[232:235], v[144:147], v[112:127]
	ds_read_b128 v[248:251], v217 offset:32896
	v_exp_f32_e32 v89, v89
	v_add_f32_e32 v176, v87, v176
	v_exp_f32_e32 v90, v90
	v_add_f32_e32 v176, v88, v176
	v_exp_f32_e32 v91, v91
	s_waitcnt lgkmcnt(3)
	v_mfma_f32_32x32x16_bf16 v[96:111], v[236:239], v[144:147], v[96:111]
	ds_read_b128 v[232:235], v217 offset:41088
	v_add_f32_e32 v176, v89, v176
	v_exp_f32_e32 v92, v92
	v_add_f32_e32 v176, v90, v176
	v_exp_f32_e32 v93, v178
	v_add_f32_e32 v176, v91, v176
	s_waitcnt lgkmcnt(3)
	v_mfma_f32_32x32x16_bf16 v[112:127], v[240:243], v[140:143], v[112:127]
	ds_read_b128 v[236:239], v218 offset:32896
	v_exp_f32_e32 v94, v179
	v_add_f32_e32 v176, v92, v176
	v_add_f32_e32 v176, v93, v176
	v_add_f32_e32 v176, v94, v176
	v_add_f32_e32 v229, v95, v176
	s_waitcnt lgkmcnt(3)
	v_mfma_f32_32x32x16_bf16 v[96:111], v[244:247], v[140:143], v[96:111]
	ds_read_b128 v[240:243], v218 offset:41088
	v_mov_b32_e32 v230, v229
	v_cvt_pk_bf16_f32 v176, v64, v65
	v_cvt_pk_bf16_f32 v177, v66, v67
	v_cvt_pk_bf16_f32 v178, v68, v69
	v_cvt_pk_bf16_f32 v179, v70, v71
	s_waitcnt lgkmcnt(3)
	v_mfma_f32_32x32x16_bf16 v[112:127], v[248:251], v[136:139], v[112:127]
	ds_read_b128 v[244:247], v219 offset:32896
	v_cvt_pk_bf16_f32 v180, v72, v73
	v_cvt_pk_bf16_f32 v181, v74, v75
	v_cvt_pk_bf16_f32 v182, v76, v77
	v_cvt_pk_bf16_f32 v183, v78, v79
	v_cvt_pk_bf16_f32 v184, v80, v81
	s_waitcnt lgkmcnt(3)
	v_mfma_f32_32x32x16_bf16 v[96:111], v[232:235], v[136:139], v[96:111]
	ds_read_b128 v[248:251], v219 offset:41088
	v_cvt_pk_bf16_f32 v185, v82, v83
	v_cvt_pk_bf16_f32 v186, v84, v85
	v_cvt_pk_bf16_f32 v187, v86, v87
	v_cvt_pk_bf16_f32 v188, v88, v89
	v_cvt_pk_bf16_f32 v189, v90, v91
	s_waitcnt lgkmcnt(3)
	v_mfma_f32_32x32x16_bf16 v[112:127], v[236:239], v[132:135], v[112:127]
	v_cvt_pk_bf16_f32 v190, v92, v93
	v_cvt_pk_bf16_f32 v191, v94, v95
	s_nop 1
	v_permlane32_swap_b32_e32 v229, v230
	v_permlane32_swap_b32_e32 v176, v178
	s_waitcnt lgkmcnt(2)
	v_mfma_f32_32x32x16_bf16 v[96:111], v[240:243], v[132:135], v[96:111]
	v_permlane32_swap_b32_e32 v177, v179
	v_permlane32_swap_b32_e32 v180, v182
	v_permlane32_swap_b32_e32 v181, v183
	v_permlane32_swap_b32_e32 v184, v186
	v_permlane32_swap_b32_e32 v185, v187
	s_waitcnt lgkmcnt(1)
	v_mfma_f32_32x32x16_bf16 v[112:127], v[244:247], v[128:131], v[112:127]
	v_permlane32_swap_b32_e32 v188, v190
	v_permlane32_swap_b32_e32 v189, v191
	s_waitcnt lgkmcnt(0)
	v_mfma_f32_32x32x16_bf16 v[96:111], v[248:251], v[128:131], v[96:111]
	s_add_i32 s3, s86, 1
	s_cmp_lt_u32 s3, s84
	s_cselect_b64 s[72:73], -1, 0
	s_cmp_ge_u32 s3, s84
	s_cbranch_scc1 .LBB0_223
	v_add_u32_e32 v160, 0x41, v228
	v_add_u32_e32 v162, 0x61, v228
	v_ashrrev_i32_e32 v161, 31, v160
	v_ashrrev_i32_e32 v163, 31, v162
	v_lshlrev_b64 v[168:169], 12, v[160:161]
	v_lshlrev_b64 v[170:171], 12, v[162:163]
	v_lshl_add_u64 v[160:161], v[200:201], 0, v[168:169]
	v_lshl_add_u64 v[164:165], v[200:201], 0, v[170:171]
	v_lshl_add_u64 v[168:169], v[202:203], 0, v[168:169]
	v_lshl_add_u64 v[172:173], v[202:203], 0, v[170:171]
	global_load_dwordx4 v[160:163], v[160:161], off
	s_nop 0
	global_load_dwordx4 v[164:167], v[164:165], off
	s_nop 0
	global_load_dwordx4 v[168:171], v[168:169], off
	s_nop 0
	global_load_dwordx4 v[172:175], v[172:173], off
